# phase 3 runs the second half of every batch's rows first (the part of proj0 written last), first half after
# baseline (speedup 1.0000x reference)
.LBB0_330:
	s_or_b64 exec, exec, s[0:1]
	s_waitcnt lgkmcnt(0)
	v_mov_b32_e32 v0, v254
	s_cmpk_gt_i32 s2, 0x7ff
	s_barrier
	s_cbranch_scc1 .LBB0_409
	v_bfe_u32 v6, v0, 5, 1
	v_ashrrev_i32_e32 v187, 5, v0
	v_lshlrev_b32_e32 v9, 9, v0
	v_lshlrev_b32_e32 v18, 3, v6
	s_movk_i32 s6, 0xff00
	v_lshlrev_b32_e32 v23, 2, v187
	v_bfe_u32 v1, v0, 2, 2
	v_lshrrev_b32_e32 v2, 3, v0
	v_bfe_u32 v4, v0, 1, 1
	v_and_b32_e32 v7, 31, v0
	v_bfe_u32 v149, v0, 6, 2
	v_ashrrev_i32_e32 v8, 8, v0
	v_and_b32_e32 v9, 0x2000, v9
	v_and_b32_e32 v10, 15, v0
	v_bfe_u32 v11, v187, 2, 2
	v_ashrrev_i32_e32 v12, 2, v0
	v_lshlrev_b32_e32 v13, 7, v0
	v_lshlrev_b32_e32 v14, 12, v0
	v_lshlrev_b32_e32 v15, 3, v0
	v_and_b32_e32 v17, 12, v0
	v_and_or_b32 v19, v0, s6, v18
	v_lshlrev_b32_e32 v0, 9, v187
	v_and_b32_e32 v23, 12, v23
	v_add_u32_e32 v9, 0, v9
	v_and_b32_e32 v21, 0xffffc000, v0
	v_lshlrev_b32_e32 v22, 8, v187
	v_bitop3_b32 v23, v23, v10, v11 bitop3:0x36
	v_add_u32_e32 v21, v9, v21
	v_and_b32_e32 v22, 0x1f00, v22
	v_lshlrev_b32_e32 v23, 4, v23
	v_add3_u32 v189, v21, v23, v22
	v_add_u32_e32 v21, 16, v187
	v_lshlrev_b32_e32 v24, 9, v21
	v_and_b32_e32 v25, 31, v21
	v_lshlrev_b32_e32 v21, 2, v21
	v_and_b32_e32 v21, 12, v21
	v_and_b32_e32 v24, 0xffffc000, v24
	v_bitop3_b32 v21, v21, v10, v11 bitop3:0x36
	v_add_u32_e32 v24, v9, v24
	v_lshlrev_b32_e32 v25, 8, v25
	v_lshlrev_b32_e32 v21, 4, v21
	v_add3_u32 v191, v24, v21, v25
	v_add_u32_e32 v21, 0x4000, v0
	v_and_b32_e32 v21, 0xffffc000, v21
	v_add_u32_e32 v21, v9, v21
	v_add3_u32 v192, v21, v23, v22
	v_add_u32_e32 v21, 48, v187
	v_lshlrev_b32_e32 v24, 9, v21
	v_and_b32_e32 v25, 31, v21
	v_lshlrev_b32_e32 v21, 2, v21
	v_and_b32_e32 v21, 12, v21
	v_and_b32_e32 v24, 0xffffc000, v24
	v_bitop3_b32 v21, v21, v10, v11 bitop3:0x36
	v_add_u32_e32 v24, v9, v24
	v_lshlrev_b32_e32 v25, 8, v25
	v_lshlrev_b32_e32 v21, 4, v21
	v_add3_u32 v193, v24, v21, v25
	v_add_u32_e32 v21, 0x8000, v0
	v_and_b32_e32 v21, 0xffffc000, v21
	v_add_u32_e32 v21, v9, v21
	v_add3_u32 v194, v21, v23, v22
	v_add_u32_e32 v21, 0x50, v187
	v_lshlrev_b32_e32 v24, 9, v21
	v_and_b32_e32 v25, 31, v21
	v_lshlrev_b32_e32 v21, 2, v21
	v_add_u32_e32 v0, 0xc000, v0
	v_and_b32_e32 v21, 12, v21
	v_and_b32_e32 v0, 0xffffc000, v0
	v_and_b32_e32 v24, 0xffffc000, v24
	v_bitop3_b32 v21, v21, v10, v11 bitop3:0x36
	v_add_u32_e32 v0, v9, v0
	v_add_u32_e32 v24, v9, v24
	v_lshlrev_b32_e32 v25, 8, v25
	v_lshlrev_b32_e32 v21, 4, v21
	v_add3_u32 v196, v0, v23, v22
	v_add_u32_e32 v0, 0x70, v187
	v_add3_u32 v195, v24, v21, v25
	v_lshlrev_b32_e32 v21, 9, v0
	v_and_b32_e32 v21, 0xffffc000, v21
	v_add_u32_e32 v9, v9, v21
	v_and_b32_e32 v21, 31, v0
	v_lshlrev_b32_e32 v0, 2, v0
	v_and_b32_e32 v0, 12, v0
	v_bitop3_b32 v0, v0, v10, v11 bitop3:0x36
	v_and_b32_e32 v15, 8, v15
	v_lshlrev_b32_e32 v16, 8, v12
	v_bfe_u32 v12, v12, 2, 2
	v_lshlrev_b32_e32 v21, 8, v21
	v_lshlrev_b32_e32 v0, 4, v0
	v_add3_u32 v197, v9, v0, v21
	v_bitop3_b32 v0, v17, v15, v12 bitop3:0x36
	v_lshlrev_b32_e32 v9, 4, v0
	v_or_b32_e32 v0, 1, v15
	v_bitop3_b32 v0, v17, v0, v12 bitop3:0x36
	v_lshlrev_b32_e32 v10, 4, v0
	v_or_b32_e32 v0, 2, v15
	v_bitop3_b32 v0, v17, v0, v12 bitop3:0x36
	v_lshlrev_b32_e32 v11, 4, v0
	v_or_b32_e32 v0, 3, v15
	v_bitop3_b32 v0, v17, v0, v12 bitop3:0x36
	v_lshlrev_b32_e32 v21, 4, v0
	v_or_b32_e32 v0, 4, v15
	v_and_b32_e32 v13, 0xffffc000, v13
	v_bitop3_b32 v0, v17, v0, v12 bitop3:0x36
	v_add_u32_e32 v13, 0, v13
	v_and_b32_e32 v14, 0x2000, v14
	v_and_b32_e32 v16, 0x1f00, v16
	v_lshlrev_b32_e32 v22, 4, v0
	v_or_b32_e32 v0, 5, v15
	v_add3_u32 v13, v13, v14, v16
	v_lshlrev_b32_e32 v14, 13, v8
	v_lshlrev_b32_e32 v16, 11, v6
	v_bitop3_b32 v0, v17, v0, v12 bitop3:0x36
	v_add3_u32 v14, 0, v14, v16
	v_lshlrev_b32_e32 v16, 8, v1
	v_lshlrev_b32_e32 v23, 4, v0
	v_or_b32_e32 v0, 6, v15
	v_and_b32_e32 v3, 2, v2
	v_add3_u32 v14, v14, v16, v15
	v_lshlrev_b32_e32 v16, 1, v6
	v_bitop3_b32 v0, v17, v0, v12 bitop3:0x36
	s_add_u32 s8, s28, 0x80000
	v_or_b32_e32 v5, v3, v4
	v_lshlrev_b32_e32 v148, 3, v7
	v_bitop3_b32 v3, v3, v16, v4 bitop3:0x36
	v_lshlrev_b32_e32 v4, 7, v8
	v_lshlrev_b32_e32 v24, 4, v0
	v_or_b32_e32 v0, 7, v15
	s_addc_u32 s9, s29, 0
	v_lshl_or_b32 v2, v149, 8, v148
	v_mov_b32_e32 v151, 0
	v_lshlrev_b32_e32 v150, 4, v7
	v_bitop3_b32 v16, v16, v5, 1 bitop3:0x36
	v_ashrrev_i32_e32 v5, 31, v4
	s_add_i32 s0, 0, 0x10000
	v_bitop3_b32 v0, v17, v0, v12 bitop3:0x36
	v_lshl_add_u64 v[152:153], s[70:71], 0, v[150:151]
	v_add_u32_e32 v20, s0, v150
	v_lshlrev_b32_e32 v12, 4, v0
	v_lshlrev_b32_e32 v200, 6, v1
	v_lshlrev_b32_e32 v150, 2, v2
	v_lshlrev_b64 v[0:1], 2, v[4:5]
	v_lshl_or_b32 v188, v149, 5, v7
	s_movk_i32 s1, 0x210
	v_mov_b32_e32 v7, s0
	v_lshl_add_u64 v[154:155], s[62:63], 0, v[150:151]
	v_lshl_add_u64 v[156:157], s[64:65], 0, v[150:151]
	v_lshl_add_u64 v[4:5], s[52:53], 0, v[0:1]
	v_lshlrev_b32_e32 v150, 4, v6
	v_lshl_add_u64 v[0:1], s[54:55], 0, v[0:1]
	v_mad_u32_u24 v7, v188, s1, v7
	v_lshl_add_u32 v198, v3, 4, v14
	v_mul_lo_u32 v3, v187, s1
	v_lshl_add_u64 v[158:159], v[4:5], 0, v[150:151]
	v_lshl_add_u64 v[160:161], v[0:1], 0, v[150:151]
	v_subrev_u32_e32 v246, s52, v158
	v_add_u32_e32 v247, 0x20c00, v246
	v_add_u32_e32 v246, 0x20800, v246
	s_mov_b64 s[98:99], exec
	v_cmp_gt_u32_e32 vcc, 64, v254
	s_and_b64 exec, exec, vcc
	v_lshlrev_b32_e32 v248, 4, v254
	global_load_dwordx4 v[250:253], v248, s[52:53]
	v_add_u32_e32 v249, 0x20800, v248
	s_waitcnt vmcnt(0)
	ds_write_b128 v249, v[250:253]
	global_load_dwordx4 v[250:253], v248, s[54:55]
	v_add_u32_e32 v249, 0x20c00, v248
	s_waitcnt vmcnt(0)
	ds_write_b128 v249, v[250:253]
	s_waitcnt lgkmcnt(0)
	s_mov_b64 exec, s[98:99]
	v_lshl_or_b32 v0, v149, 4, v6
	v_lshlrev_b32_e32 v150, 1, v2
	s_mov_b32 s13, 0
	v_cmp_lt_u32_e64 s[4:5], 1, v149
	s_mov_b32 s3, 0x10000
	s_mov_b32 s51, 0x8000
	s_mov_b32 s66, 0xc000
	v_lshl_add_u32 v199, v16, 4, v14
	v_xor_b32_e32 v201, 64, v200
	v_xor_b32_e32 v202, 0x80, v200
	v_xor_b32_e32 v203, 0xc0, v200
	v_lshl_add_u64 v[162:163], s[18:19], 0, v[150:151]
	v_lshl_or_b32 v204, v8, 4, v18
	s_lshl_b32 s53, s2, 5
	s_lshl_b32 s55, s30, 5
	s_movk_i32 s62, 0x2800
	v_lshlrev_b32_e32 v164, 1, v2
	s_mov_b64 s[24:25], 0x1800
	s_mov_b32 s63, 0xf000
	s_mov_b32 s64, 0x11000
	s_movk_i32 s65, 0x3000
	s_mov_b32 s67, 0xd000
	s_mov_b32 s70, 0x12000
	s_mov_b32 s50, 0x3e000000
	s_mov_b32 s52, 0x3e800000
	v_lshlrev_b32_e32 v205, 9, v0
	s_movk_i32 s71, 0x1000
	s_mov_b32 s72, 0x28000
	s_mov_b32 s73, 0x50000
	s_mov_b32 s74, 0x78000
	s_mov_b32 s75, 0xa0000
	s_mov_b32 s76, 0xc8000
	s_mov_b32 s77, 0xf0000
	s_mov_b32 s78, 0x118000
	v_add_u32_e32 v206, v13, v9
	v_add_u32_e32 v207, v13, v10
	v_add_u32_e32 v208, v13, v11
	v_add_u32_e32 v209, v13, v24
	v_add_u32_e32 v210, v13, v21
	v_add_u32_e32 v211, v13, v22
	v_add_u32_e32 v212, v13, v23
	v_add_u32_e32 v213, v13, v12
	s_mov_b32 s54, 0x3b800000
	s_mov_b32 s79, 0x800000
	s_mov_b32 s80, 0x29000
	s_mov_b32 s81, 0x51000
	s_mov_b32 s82, 0x79000
	s_mov_b32 s83, 0xa1000
	s_mov_b32 s84, 0xc9000
	s_mov_b32 s85, 0xf1000
	s_mov_b32 s86, 0x119000
	v_add_u32_e32 v214, v7, v19
	v_add_u32_e32 v215, v20, v3
	s_mov_b32 s87, 0x20000
	s_mov_b32 s88, 0x30000
	s_mov_b32 s89, 0x40000
	s_mov_b32 s90, 0x60000
	v_mbcnt_hi_u32_b32 v216, -1, v186
	s_mov_b32 s91, s2
	s_cmp_lg_u32 s30, 0x100
	s_cbranch_scc1 .LBB0_334
	s_mov_b32 s99, 0
	s_bfe_u32 s98, s2, 0x10003
	s_branch .Lp3_map

.LBB0_333:
	s_cmp_lg_u32 s30, 0x100
	s_cbranch_scc1 .Lp3_plain
	s_add_i32 s99, s99, 1
	s_cmp_lt_u32 s99, 8
	s_cbranch_scc0 .LBB0_409
.Lp3_map:
	s_lshr_b32 s100, s99, 1
	s_and_b32 s101, s100, 1
	s_xor_b32 s101, s101, s98
	s_lshl_b32 s91, s101, 10
	s_cmp_lt_u32 s100, 2
	s_cselect_b32 s100, 64, 0
	s_or_b32 s91, s91, s100
	s_and_b32 s100, s99, 1
	s_lshl_b32 s100, s100, 8
	s_or_b32 s100, s100, s2
	s_and_b32 s101, s100, 63
	s_or_b32 s91, s91, s101
	s_lshr_b32 s100, s100, 6
	s_lshl_b32 s100, s100, 7
	s_or_b32 s91, s91, s100
	s_lshl_b32 s53, s91, 5
	s_branch .LBB0_334

.LBB0_883:
	s_add_i32 s57, s57, 2
	s_and_b64 vcc, exec, s[12:13]
	s_nop 0
	s_add_u32 s8, s8, 0xc000
	s_addc_u32 s9, s9, 0
	s_waitcnt vmcnt(0) lgkmcnt(0)
	s_barrier
	s_cbranch_vccnz .LBB0_893
